# norm phases (bf16 residual): the wave's other three rows are requested into dead registers right after the first row's loads
# baseline (speedup 1.0000x reference)
; #define GAS __attribute__((address_space(1)))
; #define ARG_IN(i) ((const float*)karg64(8 * (i)))
; #define ARG_WS() ((unsigned char*)karg64(8 * 19))
; #define REP(k) for (int rep_ = 0; rep_ < (DUP_PHASE == (k) ? 2 : 1); ++rep_, (DUP_PHASE == (k) ? xcd_barrier(bar) : (void)0))
; #define IDX() int tid = threadIdx.x, bid = blockIdx.x, G = gridDim.x; asm volatile("" : "+v"(tid)); asm volatile("" : "+s"(bid), "+s"(G)); \
;     const int lane = tid & 63, wave = __builtin_amdgcn_readfirstlane(tid >> 6), gw = bid * NWAVES + wave, NGW = G * NWAVES; (void)lane; (void)gw; (void)NGW; (void)wave
; __device__ __forceinline__ void norm_mod_rows_b(const bf16* src, const float* gain, const float* sh, const float* sc, bf16* dst, int gw, int NGW, int lane) {
;     v4u cur[4], nxt[4]; f32x4 A[8], B[8]; int cb = -1;
;     if (gw < M) { const GAS v4u* xr = (const GAS v4u*)(src + (size_t)gw * DM) + lane;
; #pragma unroll
;         for (int j = 0; j < 4; ++j) cur[j] = xr[64 * j]; }
; #pragma unroll 1
;     for (int m = gw; m < M; m += NGW) { const int b = m >> 12; const int mn = m + NGW < M ? m + NGW : m;
;         { const GAS v4u* xr = (const GAS v4u*)(src + (size_t)mn * DM) + lane;
; #pragma unroll
;             for (int j = 0; j < 4; ++j) nxt[j] = xr[64 * j]; }
; template <int PHM, int ATTM> __global__ void __launch_bounds__(NWAVES * 64, 2) fwd_kernel(Args args) {
;     ...
;         REP(1) if (IN(pb + 0) && EN(1)) { IDX(); unsigned char* ws = ARG_WS(); const float* mod = WSP(float, WS_MOD) + (size_t)layer * BATCH * NADA;
;             if (layer == 0) norm_mod_rows(ARG_IN(A_X), ARG_IN(A_GMIX) + (size_t)layer * DM, mod + 0, mod + DM, WSP(bf16, WS_U), gw, NGW, lane);
;             else norm_mod_rows_b(WSP(bf16, WS_H), ARG_IN(A_GMIX) + (size_t)layer * DM, mod + 0, mod + DM, WSP(bf16, WS_U), gw, NGW, lane); }
.LBB0_240:
	s_mul_i32 s2, s6, 9
	s_add_i32 s4, s2, 1
	s_cmp_le_i32 s68, s4
	v_writelane_b32 v255, s2, 20
	s_cselect_b64 s[2:3], -1, 0
	s_cmp_lt_i32 s4, s67
	s_mov_b32 s7, s19
	s_cselect_b64 s[4:5], -1, 0
	v_writelane_b32 v255, s6, 21
	s_and_b64 s[2:3], s[2:3], s[4:5]
	s_lshl_b64 s[4:5], s[6:7], 13
	v_writelane_b32 v255, s7, 22
	v_writelane_b32 v255, s4, 23
	s_andn2_b64 vcc, exec, s[2:3]
	s_nop 0
	v_writelane_b32 v255, s5, 24
	s_cbranch_vccnz .LBB0_254
	s_load_dword s5, s[72:73], 0x0
	v_mov_b32_e32 v1, v0
	s_mov_b32 s7, s66
	s_waitcnt lgkmcnt(0)
	s_load_dwordx2 s[22:23], s[0:1], 0x98
	v_readfirstlane_b32 s8, v1
	v_readlane_b32 s10, v255, 21
	s_ashr_i32 s8, s8, 6
	s_lshl_b32 s7, s7, 3
	s_mul_i32 s6, s10, 0x18000
	s_add_i32 s16, s7, s8
	s_lshl_b32 s14, s5, 3
	s_mul_hi_u32 s4, s10, 0x18000
	s_waitcnt lgkmcnt(0)
	s_add_u32 s5, s22, s6
	s_addc_u32 s6, s23, s4
	s_add_u32 s4, s5, 0x100000
	s_addc_u32 s5, s6, 0
	s_cmp_lg_u32 s10, 0
	s_waitcnt vmcnt(0)
	v_and_b32_e32 v100, 63, v1
	v_readlane_b32 s11, v255, 22
	s_cbranch_scc0 .LBB0_248
	s_load_dwordx2 s[20:21], s[0:1], 0x20
	s_cmpk_gt_i32 s16, 0x1fff
	s_cbranch_scc1 .LBB0_247
	s_add_u32 s6, s22, 0x4800000
	s_addc_u32 s7, s23, 0
	s_add_u32 s8, s4, 0x2000
	s_addc_u32 s9, s5, 0
	v_readlane_b32 s10, v255, 23
	v_readlane_b32 s11, v255, 24
	s_waitcnt lgkmcnt(0)
	s_add_u32 s10, s20, s10
	s_addc_u32 s11, s21, s11
	s_ashr_i32 s17, s16, 31
	s_lshl_b64 s[12:13], s[16:17], 12
	s_add_u32 s20, s6, s12
	s_addc_u32 s21, s7, s13
	v_lshlrev_b32_e32 v2, 4, v100
	global_load_dwordx4 v[32:35], v2, s[20:21]
	global_load_dwordx4 v[28:31], v2, s[20:21] offset:1024
	global_load_dwordx4 v[24:27], v2, s[20:21] offset:2048
	global_load_dwordx4 v[20:23], v2, s[20:21] offset:3072
	s_add_u32 s30, s20, 0x800000
	s_addc_u32 s31, s21, 0
	global_load_dwordx4 v[146:149], v2, s[30:31]
	global_load_dwordx4 v[150:153], v2, s[30:31] offset:1024
	global_load_dwordx4 v[154:157], v2, s[30:31] offset:2048
	global_load_dwordx4 v[158:161], v2, s[30:31] offset:3072
	s_add_u32 s30, s30, 0x800000
	s_addc_u32 s31, s31, 0
	global_load_dwordx4 v[146:149], v2, s[30:31]
	global_load_dwordx4 v[150:153], v2, s[30:31] offset:1024
	global_load_dwordx4 v[154:157], v2, s[30:31] offset:2048
	global_load_dwordx4 v[158:161], v2, s[30:31] offset:3072
	s_add_u32 s30, s30, 0x800000
	s_addc_u32 s31, s31, 0
	global_load_dwordx4 v[146:149], v2, s[30:31]
	global_load_dwordx4 v[150:153], v2, s[30:31] offset:1024
	global_load_dwordx4 v[154:157], v2, s[30:31] offset:2048
	global_load_dwordx4 v[158:161], v2, s[30:31] offset:3072
	v_lshlrev_b32_e32 v4, 3, v100
	v_lshlrev_b32_e32 v6, 5, v100
	v_mov_b32_e32 v7, v3
	v_lshl_add_u64 v[102:103], s[10:11], 0, v[6:7]
	v_or_b32_e32 v6, 0x400, v4
	v_lshlrev_b32_e32 v8, 2, v6
	v_mov_b32_e32 v9, v3
	v_lshl_add_u64 v[104:105], s[10:11], 0, v[8:9]
	v_or_b32_e32 v8, 0x600, v4
	v_lshlrev_b32_e32 v10, 2, v8
	v_mov_b32_e32 v11, v3
	v_lshl_add_u64 v[106:107], s[10:11], 0, v[10:11]
	s_add_u32 s10, s22, s12
	s_addc_u32 s11, s23, s13
	v_lshl_add_u64 v[10:11], s[10:11], 0, v[2:3]
	s_mov_b64 s[10:11], 0x800000
	s_ashr_i32 s15, s14, 31
	v_lshl_add_u64 v[108:109], v[10:11], 0, s[10:11]
	s_lshl_b64 s[20:21], s[14:15], 12
	s_mov_b32 s12, -1
	v_lshlrev_b32_e32 v1, 4, v100
	v_lshlrev_b32_e32 v2, 2, v4
	v_lshlrev_b32_e32 v101, 2, v6
	v_lshlrev_b32_e32 v110, 2, v8
	s_mov_b32 s10, s16
	s_branch .LBB0_245

; #define GAS __attribute__((address_space(1)))
; #define ARG_IN(i) ((const float*)karg64(8 * (i)))
; #define ARG_WS() ((unsigned char*)karg64(8 * 19))
; #define IDX() int tid = threadIdx.x, bid = blockIdx.x, G = gridDim.x; asm volatile("" : "+v"(tid)); asm volatile("" : "+s"(bid), "+s"(G)); \
;     const int lane = tid & 63, wave = __builtin_amdgcn_readfirstlane(tid >> 6), gw = bid * NWAVES + wave, NGW = G * NWAVES; (void)lane; (void)gw; (void)NGW; (void)wave
; __device__ __forceinline__ void norm_mod_rows_b(const bf16* src, const float* gain, const float* sh, const float* sc, bf16* dst, int gw, int NGW, int lane) {
;     v4u cur[4], nxt[4]; f32x4 A[8], B[8]; int cb = -1;
;     if (gw < M) { const GAS v4u* xr = (const GAS v4u*)(src + (size_t)gw * DM) + lane;
; #pragma unroll
;         for (int j = 0; j < 4; ++j) cur[j] = xr[64 * j]; }
; #pragma unroll 1
;     for (int m = gw; m < M; m += NGW) { const int b = m >> 12; const int mn = m + NGW < M ? m + NGW : m;
;         { const GAS v4u* xr = (const GAS v4u*)(src + (size_t)mn * DM) + lane;
; #pragma unroll
;             for (int j = 0; j < 4; ++j) nxt[j] = xr[64 * j]; }
; template <int PHM, int ATTM> __global__ void __launch_bounds__(NWAVES * 64, 2) fwd_kernel(Args args) {
;     ...
;         if (IN(pb + 6) && EN(7)) { IDX(); unsigned char* ws = ARG_WS(); const float* mod = WSP(float, WS_MOD) + (size_t)layer * BATCH * NADA;
;             norm_mod_rows_b(WSP(bf16, WS_H), ARG_IN(A_GFFN) + (size_t)layer * DM, mod + 3 * DM, mod + 4 * DM, WSP(bf16, WS_U), gw, NGW, lane); }
.LBB0_2103:
	s_andn2_b64 vcc, exec, s[2:3]
	s_cbranch_vccnz .LBB0_2155
	s_load_dword s3, s[72:73], 0x0
	v_mov_b32_e32 v1, v0
	s_mov_b32 s2, s66
	s_waitcnt lgkmcnt(0)
	s_load_dwordx2 s[16:17], s[0:1], 0x98
	s_load_dwordx2 s[20:21], s[0:1], 0x28
	v_readfirstlane_b32 s4, v1
	s_ashr_i32 s10, s4, 6
	s_lshl_b32 s11, s2, 3
	s_add_i32 s2, s11, s10
	s_cmpk_gt_i32 s2, 0x1fff
	s_cbranch_scc1 .LBB0_2109
	v_readlane_b32 s4, v255, 21
	s_lshl_b32 s14, s3, 3
	s_mul_hi_u32 s3, s4, 0x18000
	s_mul_i32 s4, s4, 0x18000
	s_waitcnt lgkmcnt(0)
	s_add_u32 s8, s16, s4
	s_addc_u32 s3, s17, s3
	v_readlane_b32 s5, v255, 22
	s_add_u32 s4, s16, 0x4800000
	s_addc_u32 s5, s17, 0
	s_add_u32 s6, s8, 0x106000
	s_addc_u32 s7, s3, 0
	s_add_u32 s8, s8, 0x108000
	s_addc_u32 s9, s3, 0
	v_readlane_b32 s12, v255, 23
	v_readlane_b32 s13, v255, 24
	s_add_u32 s12, s20, s12
	s_addc_u32 s13, s21, s13
	s_ashr_i32 s3, s2, 31
	s_lshl_b64 s[20:21], s[2:3], 12
	v_and_b32_e32 v4, 63, v1
	s_add_u32 s20, s4, s20
	s_addc_u32 s21, s5, s21
	v_lshlrev_b32_e32 v2, 4, v4
	global_load_dwordx4 v[32:35], v2, s[20:21]
	global_load_dwordx4 v[28:31], v2, s[20:21] offset:1024
	global_load_dwordx4 v[24:27], v2, s[20:21] offset:2048
	global_load_dwordx4 v[20:23], v2, s[20:21] offset:3072
	s_add_u32 s30, s20, 0x800000
	s_addc_u32 s31, s21, 0
	global_load_dwordx4 v[146:149], v2, s[30:31]
	global_load_dwordx4 v[150:153], v2, s[30:31] offset:1024
	global_load_dwordx4 v[154:157], v2, s[30:31] offset:2048
	global_load_dwordx4 v[158:161], v2, s[30:31] offset:3072
	s_add_u32 s30, s30, 0x800000
	s_addc_u32 s31, s31, 0
	global_load_dwordx4 v[146:149], v2, s[30:31]
	global_load_dwordx4 v[150:153], v2, s[30:31] offset:1024
	global_load_dwordx4 v[154:157], v2, s[30:31] offset:2048
	global_load_dwordx4 v[158:161], v2, s[30:31] offset:3072
	s_add_u32 s30, s30, 0x800000
	s_addc_u32 s31, s31, 0
	global_load_dwordx4 v[146:149], v2, s[30:31]
	global_load_dwordx4 v[150:153], v2, s[30:31] offset:1024
	global_load_dwordx4 v[154:157], v2, s[30:31] offset:2048
	global_load_dwordx4 v[158:161], v2, s[30:31] offset:3072
	v_lshlrev_b32_e32 v6, 3, v4
	v_lshlrev_b32_e32 v8, 5, v4
	v_mov_b32_e32 v9, v3
	s_waitcnt vmcnt(0)
	v_lshl_add_u64 v[100:101], s[12:13], 0, v[8:9]
	v_or_b32_e32 v8, 0x400, v6
	v_lshlrev_b32_e32 v10, 2, v8
	v_mov_b32_e32 v11, v3
	v_lshl_add_u64 v[102:103], s[12:13], 0, v[10:11]
	v_or_b32_e32 v10, 0x600, v6
	v_lshlrev_b32_e32 v12, 2, v10
	v_mov_b32_e32 v13, v3
	v_lshl_add_u64 v[104:105], s[12:13], 0, v[12:13]
	s_ashr_i32 s3, s10, 31
	s_ashr_i32 s12, s11, 31
	s_add_u32 s10, s10, s11
	s_addc_u32 s11, s3, s12
	s_lshl_b64 s[10:11], s[10:11], 12
	s_add_u32 s10, s16, s10
	s_addc_u32 s11, s17, s11
	v_lshl_add_u64 v[12:13], s[10:11], 0, v[2:3]
	s_mov_b64 s[10:11], 0x800000
	s_ashr_i32 s15, s14, 31
	v_lshl_add_u64 v[106:107], v[12:13], 0, s[10:11]
	s_lshl_b64 s[16:17], s[14:15], 12
	s_mov_b32 s10, -1
	v_lshlrev_b32_e32 v1, 4, v4
	v_lshlrev_b32_e32 v2, 2, v6
	v_lshlrev_b32_e32 v108, 2, v8
	v_lshlrev_b32_e32 v109, 2, v10
	s_branch .LBB0_2107
